# GLA scan step: the 18 operand ds_reads are issued right after the step barrier and the two-steps-ahead prefetch global loads with their address math follow them (7 of 8 step instances); on top of v64
# speedup vs baseline: 1.0089x; 1.0057x over previous
; #define LAS __attribute__((address_space(3)))
; template <bool SAMP> __device__ __forceinline__ void h2_load(H2Regs& R, const Args& a, const H2Off& O, int row0, int uid, int h, int es, int tid, int lane) {
;     const char* bA = (const char*)(a.ws + WS_ABUF) + ((size_t)row0 * 256 + h * 64) * 2;
;     const char* bQ = (const char*)(a.ws + WS_T0) + ((size_t)row0 * D + h * 128) * 2;
;     const char* bK = (const char*)(a.ws + WS_T7) + (size_t)uid * 16384;
;     const char* bV = (const char*)(a.ws + WS_T1) + ((size_t)row0 * D + h * 256 + es * 64) * 2;
;     const char* bG = (const char*)(a.ws + WS_GDEC) + (size_t)uid * 512;
;     const v4u z = {0u, 0u, 0u, 0u};
;     R.a = z; if (!SAMP || (tid >> 3) < DEC_T) R.a = *(const v4u*)(bA + O.a);
; #pragma unroll
;     for (int j = 0; j < 2; ++j) { R.q[j] = z; if (!SAMP || j == 0) R.q[j] = *(const v4u*)(bQ + O.q + j * 65536); }
; #pragma unroll
;     for (int j = 0; j < 2; ++j) R.kt[j] = *(const v4u*)(bK + O.k + j * 8192);
;     R.v = z; if (!SAMP || lane < DEC_T) R.v = *(const v4u*)(bV + O.v);
;     R.g4 = *(const f32x4*)(bG + O.g);
; }
; __device__ __forceinline__ void h2_stage(const H2Regs& R, LAS unsigned char* lds, int tid, int lane, int wave) {
;     { const int t = tid >> 3, ch = tid & 7; *(LAS v4u*)(lds + H2_A_OFF + t * H2_A_LD + ch * 16) = R.a; }
; #pragma unroll
;     for (int j = 0; j < 2; ++j) { const int p = tid + 512 * j; *(LAS v4u*)(lds + H2_Q_OFF + (p >> 4) * H2_Q_LD + (p & 15) * 16) = R.q[j]; *(LAS v4u*)(lds + H2_KT_OFF + (p >> 3) * H2_KT_LD + (p & 7) * 16) = R.kt[j]; }
;     { LAS unsigned short* vt = (LAS unsigned short*)(lds + H2_VT_OFF + (wave * 8) * H2_VT_LD + lane * 2); const unsigned w_[4] = {R.v.x, R.v.y, R.v.z, R.v.w};
; #pragma unroll
;       for (int i = 0; i < 4; ++i) { vt[(2 * i) * (H2_VT_LD / 2)] = (unsigned short)(w_[i] & 0xffffu); vt[(2 * i + 1) * (H2_VT_LD / 2)] = (unsigned short)(w_[i] >> 16); } }
.LBB0_1355:
	s_lshl_b32 s10, s44, 1
	s_and_b32 s21, s10, 0x180
	s_ashr_i32 s10, s54, 4
	s_ashr_i32 s20, s54, 2
	s_lshl_b32 s28, s10, 12
	s_and_b32 s56, s20, 3
	s_lshl_b32 s10, s10, 8
	s_ashr_i32 s29, s28, 31
	s_or_b32 s30, s10, s56
	s_lshl_b32 s10, s56, 7
	s_lshl_b64 s[34:35], s[28:29], 9
	s_add_u32 s22, s1, s34
	s_addc_u32 s23, s41, s35
	s_add_u32 s22, s22, s10
	s_addc_u32 s23, s23, 0
	s_lshl_b64 s[36:37], s[28:29], 10
	s_ashr_i32 s31, s30, 31
	s_or_b32 s24, s36, s10
	s_mov_b32 s25, s37
	s_lshl_b64 s[26:27], s[30:31], 14
	v_lshl_add_u64 v[4:5], s[22:23], 0, v[82:83]
	s_lshl_b32 s22, s54, 6
	v_lshl_add_u64 v[12:13], s[24:25], 1, v[90:91]
	v_lshl_add_u64 v[20:21], v[92:93], 0, s[26:27]
	s_lshl_b32 s26, s56, 8
	s_and_b32 s24, s22, 0xc0
	global_load_dwordx4 v[4:7], v[4:5], off
	s_nop 0
	global_load_dwordx4 v[8:11], v[12:13], off
	v_add_co_u32_e32 v12, vcc, s0, v12
	s_or_b32 s22, s26, s24
	s_nop 0
	v_addc_co_u32_e32 v13, vcc, 0, v13, vcc
	s_or_b32 s36, s36, s22
	global_load_dwordx4 v[12:15], v[12:13], off
	s_nop 0
	global_load_dwordx4 v[16:19], v[20:21], off
	v_add_co_u32_e32 v20, vcc, s46, v20
	s_lshl_b64 s[58:59], s[30:31], 9
	s_lshl_b64 s[38:39], s[36:37], 1
	v_addc_co_u32_e32 v21, vcc, 0, v21, vcc
	v_lshl_add_u64 v[24:25], v[94:95], 0, s[38:39]
	v_lshl_add_u64 v[22:23], v[96:97], 0, s[58:59]
	global_load_dwordx4 v[28:31], v[22:23], off
	s_nop 0
	global_load_dwordx4 v[20:23], v[20:21], off
	s_nop 0
	global_load_dwordx4 v[24:27], v[24:25], off
	s_or_b32 s36, s28, 64
	s_ashr_i32 s37, s36, 31
	s_or_b32 s58, s30, 4
	s_lshl_b64 s[60:61], s[36:37], 9
	s_add_u32 s23, s1, s60
	s_addc_u32 s25, s41, s61
	s_add_u32 s60, s23, s10
	s_addc_u32 s61, s25, 0
	s_ashr_i32 s59, s58, 31
	s_lshl_b64 s[62:63], s[58:59], 14
	s_lshl_b64 s[58:59], s[58:59], 9
	s_lshl_b64 s[36:37], s[36:37], 10
	v_lshl_add_u64 v[42:43], v[96:97], 0, s[58:59]
	s_or_b32 s58, s28, 0x80
	v_lshl_add_u64 v[32:33], s[60:61], 0, v[82:83]
	s_or_b32 s60, s36, s10
	s_mov_b32 s61, s37
	s_or_b32 s36, s36, s22
	s_ashr_i32 s59, s58, 31
	v_lshl_add_u64 v[36:37], s[60:61], 1, v[90:91]
	v_lshl_add_u64 v[40:41], v[92:93], 0, s[62:63]
	s_lshl_b64 s[36:37], s[36:37], 1
	s_or_b32 s60, s30, 8
	s_lshl_b64 s[62:63], s[58:59], 9
	v_add_co_u32_e32 v44, vcc, s0, v36
	s_add_u32 s23, s1, s62
	s_nop 0
	v_addc_co_u32_e32 v45, vcc, 0, v37, vcc
	s_addc_u32 s25, s41, s63
	v_add_co_u32_e32 v46, vcc, s46, v40
	s_add_u32 s62, s23, s10
	global_load_dwordx4 v[32:35], v[32:33], off
	v_addc_co_u32_e32 v47, vcc, 0, v41, vcc
	v_lshl_add_u64 v[48:49], v[94:95], 0, s[36:37]
	global_load_dwordx4 v[36:39], v[36:37], off
	s_nop 0
	global_load_dwordx4 v[52:55], v[44:45], off
	global_load_dwordx4 v[64:67], v[40:41], off
	global_load_dwordx4 v[68:71], v[46:47], off
	global_load_dwordx4 v[72:75], v[48:49], off
	global_load_dwordx4 v[60:63], v[42:43], off
	s_waitcnt lgkmcnt(0)
	s_barrier
	v_add_u32_e32 v158, v131, v132
	s_addc_u32 s63, s25, 0
	s_lshl_b64 s[58:59], s[58:59], 10
	v_add_u32_e32 v154, v125, v127
	v_add_u32_e32 v155, v126, v124
	v_add_u32_e32 v156, v125, v128
	v_add_u32_e32 v157, v126, v129
	v_add_u32_e32 v153, s33, v130
	s_or_b32 s64, s58, s10
	s_mov_b32 s65, s59
	s_ashr_i32 s61, s60, 31
	s_waitcnt vmcnt(7)
	ds_write_b128 v143, v[4:7]
	ds_write_b128 v154, v[8:11] offset:10240
	ds_write_b128 v155, v[16:19] offset:28672
	ds_write_b128 v156, v[12:15] offset:10240
	ds_write_b128 v157, v[20:23] offset:28672
	ds_write_b16 v153, v24 offset:49152
	ds_write_b16_d16_hi v153, v24 offset:49312
	ds_write_b16 v153, v25 offset:49472
	ds_write_b16_d16_hi v153, v25 offset:49632
	ds_write_b16 v153, v26 offset:49792
	ds_write_b16_d16_hi v153, v26 offset:49952
	ds_write_b16 v153, v27 offset:50112
	ds_write_b16_d16_hi v153, v27 offset:50272
	ds_write2st64_b64 v158, v[108:109], v[108:109] offset0:116 offset1:125
	ds_write2st64_b64 v144, v[108:109], v[108:109] offset0:116 offset1:125
	s_waitcnt lgkmcnt(0)
	s_barrier
	v_add_u32_e32 v166, v133, v134
	v_add_u32_e32 v160, v135, v136
	v_add_u32_e32 v159, v135, v137
	ds_read_b128 v[8:11], v166
	ds_read_b128 v[12:15], v166 offset:64
	ds_read_b128 v[16:19], v145 offset:10240
	ds_read_b128 v[76:79], v145 offset:10304
	ds_read_b128 v[110:113], v145 offset:10368
	ds_read_b128 v[114:117], v145 offset:10432
	ds_read_b128 v[118:121], v160 offset:49152
	ds_read_b128 v[162:165], v160 offset:49216
	ds_read_b128 v[168:171], v159 offset:59392
	ds_read_b128 v[172:175], v159 offset:59456
	ds_read_b128 v[176:179], v159 offset:59520
	ds_read_b128 v[180:183], v159 offset:59584
	ds_read_b128 v[184:187], v160 offset:51712
	ds_read_b128 v[188:191], v160 offset:51776
	ds_read_b128 v[192:195], v159 offset:64000
	ds_read_b128 v[196:199], v159 offset:64064
	ds_read_b128 v[200:203], v159 offset:64128
	ds_read_b128 v[204:207], v159 offset:64192
	v_lshl_add_u64 v[4:5], s[62:63], 0, v[82:83]
	v_lshl_add_u64 v[6:7], s[64:65], 1, v[90:91]
	s_lshl_b64 s[66:67], s[60:61], 14
	global_load_dwordx4 v[20:23], v[4:5], off
	global_load_dwordx4 v[24:27], v[6:7], off
	v_add_co_u32_e32 v4, vcc, s0, v6
	s_lshl_b64 s[60:61], s[60:61], 9
	s_nop 0
	v_addc_co_u32_e32 v5, vcc, 0, v7, vcc
	v_lshl_add_u64 v[6:7], v[92:93], 0, s[66:67]
	global_load_dwordx4 v[40:43], v[4:5], off
	global_load_dwordx4 v[44:47], v[6:7], off
	v_add_co_u32_e32 v4, vcc, s46, v6
	s_or_b32 s58, s58, s22
	s_nop 0
	v_addc_co_u32_e32 v5, vcc, 0, v7, vcc
	v_lshl_add_u64 v[6:7], s[58:59], 1, v[94:95]
	global_load_dwordx4 v[56:59], v[4:5], off
	global_load_dwordx4 v[48:51], v[6:7], off
	v_lshl_add_u64 v[4:5], v[96:97], 0, s[60:61]
	global_load_dwordx4 v[4:7], v[4:5], off
	s_waitcnt lgkmcnt(0)
	s_mov_b32 s23, s11
	s_waitcnt lgkmcnt(11)
	v_mfma_f32_16x16x32_bf16 v[118:121], v[118:121], v[8:11], 0
	s_waitcnt lgkmcnt(5)
; #define LAS __attribute__((address_space(3)))
; __device__ __forceinline__ void h2_stage(const H2Regs& R, LAS unsigned char* lds, int tid, int lane, int wave) {
;     { const int t = tid >> 3, ch = tid & 7; *(LAS v4u*)(lds + H2_A_OFF + t * H2_A_LD + ch * 16) = R.a; }
; #pragma unroll
;     for (int j = 0; j < 2; ++j) { const int p = tid + 512 * j; *(LAS v4u*)(lds + H2_Q_OFF + (p >> 4) * H2_Q_LD + (p & 15) * 16) = R.q[j]; *(LAS v4u*)(lds + H2_KT_OFF + (p >> 3) * H2_KT_LD + (p & 7) * 16) = R.kt[j]; }
;     { LAS unsigned short* vt = (LAS unsigned short*)(lds + H2_VT_OFF + (wave * 8) * H2_VT_LD + lane * 2); const unsigned w_[4] = {R.v.x, R.v.y, R.v.z, R.v.w};
; #pragma unroll
;       for (int i = 0; i < 4; ++i) { vt[(2 * i) * (H2_VT_LD / 2)] = (unsigned short)(w_[i] & 0xffffu); vt[(2 * i + 1) * (H2_VT_LD / 2)] = (unsigned short)(w_[i] >> 16); } }
	v_mfma_f32_16x16x32_bf16 v[8:11], v[184:187], v[8:11], 0
	s_waitcnt lgkmcnt(4)
	v_mfma_f32_16x16x32_bf16 v[8:11], v[188:191], v[12:15], v[8:11]
	s_waitcnt lgkmcnt(3)
	v_mfma_f32_16x16x32_bf16 v[8:11], v[192:195], v[16:19], v[8:11]
	s_waitcnt lgkmcnt(2)
	v_mfma_f32_16x16x32_bf16 v[8:11], v[196:199], v[76:79], v[8:11]
	s_waitcnt lgkmcnt(1)
	v_mfma_f32_16x16x32_bf16 v[8:11], v[200:203], v[110:113], v[8:11]
	s_waitcnt lgkmcnt(0)
	v_mfma_f32_16x16x32_bf16 v[8:11], v[204:207], v[114:117], v[8:11]
	v_mfma_f32_16x16x32_bf16 v[118:121], v[162:165], v[12:15], v[118:121]
	v_mfma_f32_16x16x32_bf16 v[12:15], v[168:171], v[16:19], v[118:121]
	v_add_u32_e32 v161, v135, v138
	ds_read_b128 v[16:19], v146 offset:28672
	s_nop 4
	ds_read_b128 v[118:121], v146 offset:28736
	v_pk_mul_f32 v[30:31], v[30:31], 0 op_sel_hi:[1,0]
	v_mfma_f32_16x16x32_bf16 v[12:15], v[172:175], v[76:79], v[12:15]
	ds_read_b128 v[76:79], v161 offset:49152
	ds_read_b128 v[168:171], v161 offset:49216
	ds_read_b128 v[162:165], v161 offset:51712
	ds_read_b128 v[172:175], v161 offset:51776
	v_pk_mul_f32 v[28:29], v[28:29], 0 op_sel_hi:[1,0]
	v_mfma_f32_16x16x32_bf16 v[12:15], v[176:179], v[110:113], v[12:15]
	ds_read_b128 v[110:113], v161 offset:54272
	ds_read_b128 v[176:179], v161 offset:54336
	ds_read_b128 v[184:187], v161 offset:56832
	ds_read_b128 v[188:191], v161 offset:56896
	s_waitcnt lgkmcnt(0)
	v_mfma_f32_16x16x32_bf16 v[12:15], v[180:183], v[114:117], v[12:15]
	s_nop 7
	v_cvt_pk_bf16_f32 v114, v12, v13
	v_cvt_pk_bf16_f32 v115, v14, v15
	s_waitcnt lgkmcnt(7)
	v_mfma_f32_16x16x32_bf16 v[12:15], v[16:19], v[76:79], v[28:31]
	v_lshl_add_u64 v[116:117], v[98:99], 0, s[38:39]
	v_cvt_pk_bf16_f32 v8, v8, v9
	v_cvt_pk_bf16_f32 v9, v10, v11
	s_waitcnt lgkmcnt(5)
	v_mfma_f32_16x16x32_bf16 v[76:79], v[16:19], v[162:165], v[28:31]
	global_store_dwordx2 v[116:117], v[8:9], off offset:32
	global_store_dwordx2 v[116:117], v[114:115], off
	s_waitcnt vmcnt(9)
	s_waitcnt lgkmcnt(3)
	v_mfma_f32_16x16x32_bf16 v[8:11], v[16:19], v[110:113], v[28:31]
	v_add_u32_e32 v162, v139, v127
	v_add_u32_e32 v163, v140, v124
	v_add_u32_e32 v164, v139, v128
	s_waitcnt lgkmcnt(1)
	v_mfma_f32_16x16x32_bf16 v[16:19], v[16:19], v[184:187], v[28:31]
	v_add_u32_e32 v165, v140, v129
	s_or_b32 s38, s28, 0xc0
	ds_write_b128 v147, v[32:35]
	ds_write_b128 v162, v[36:39]
	ds_write_b128 v163, v[64:67]
	v_mfma_f32_16x16x32_bf16 v[64:67], v[118:121], v[168:171], v[12:15]
	ds_write_b128 v164, v[52:55]
	ds_write_b128 v165, v[68:71]
	s_ashr_i32 s39, s38, 31
	v_mfma_f32_16x16x32_bf16 v[68:71], v[118:121], v[172:175], v[76:79]
	s_or_b32 s58, s30, 12
	s_lshl_b64 s[60:61], s[38:39], 9
	s_add_u32 s25, s1, s60
	v_mfma_f32_16x16x32_bf16 v[76:79], v[118:121], v[176:179], v[8:11]
	s_addc_u32 s27, s41, s61
	v_add_u32_e32 v3, s40, v130
	s_add_u32 s60, s25, s10
	s_waitcnt lgkmcnt(5)
	v_mfma_f32_16x16x32_bf16 v[110:113], v[118:121], v[188:191], v[16:19]
	v_cvt_pk_bf16_f32 v8, v64, v65
	v_cvt_pk_bf16_f32 v9, v66, v67
	v_cvt_pk_bf16_f32 v10, v68, v69
	v_cvt_pk_bf16_f32 v11, v70, v71
	ds_write_b16 v3, v72
	ds_write_b16_d16_hi v3, v72 offset:160
	ds_write_b16 v3, v73 offset:320
	ds_write_b16_d16_hi v3, v73 offset:480
	ds_write_b16 v3, v74 offset:640
	ds_write_b16_d16_hi v3, v74 offset:800
	ds_write_b16 v3, v75 offset:960
	ds_write_b16_d16_hi v3, v75 offset:1120
	ds_write2st64_b64 v148, v[8:9], v[10:11] offset1:9
	v_cvt_pk_bf16_f32 v8, v76, v77
	v_cvt_pk_bf16_f32 v9, v78, v79
	v_cvt_pk_bf16_f32 v10, v110, v111
	v_cvt_pk_bf16_f32 v11, v112, v113
	s_addc_u32 s61, s27, 0
	s_lshl_b64 s[38:39], s[38:39], 10
	ds_write2st64_b64 v148, v[8:9], v[10:11] offset0:18 offset1:27
	s_or_b32 s62, s38, s10
	s_mov_b32 s63, s39
	s_waitcnt lgkmcnt(0)
	s_barrier
	v_add_u32_e32 v168, v141, v136
	ds_read_b128 v[72:75], v149
	ds_read_b128 v[114:117], v149 offset:64
	ds_read_b128 v[118:121], v150
	ds_read_b128 v[170:173], v150 offset:64
	ds_read_b128 v[174:177], v150 offset:128
	ds_read_b128 v[178:181], v150 offset:192
	ds_read_b128 v[182:185], v168
	ds_read_b128 v[186:189], v168 offset:64
	ds_read_b128 v[190:193], v151
	ds_read_b128 v[194:197], v151 offset:64
	ds_read_b128 v[198:201], v151 offset:128
	ds_read_b128 v[202:205], v151 offset:192
	ds_read_b128 v[206:209], v168 offset:2560
	ds_read_b128 v[210:213], v168 offset:2624
	ds_read_b128 v[214:217], v151 offset:4608
	ds_read_b128 v[218:221], v151 offset:4672
	ds_read_b128 v[222:225], v151 offset:4736
	ds_read_b128 v[226:229], v151 offset:4800
	s_ashr_i32 s59, s58, 31
	v_lshl_add_u64 v[8:9], s[60:61], 0, v[82:83]
	v_lshl_add_u64 v[10:11], s[62:63], 1, v[90:91]
	s_lshl_b64 s[64:65], s[58:59], 14
	global_load_dwordx4 v[12:15], v[8:9], off
	global_load_dwordx4 v[16:19], v[10:11], off
	v_add_co_u32_e32 v8, vcc, s0, v10
	s_lshl_b64 s[58:59], s[58:59], 9
	s_nop 0
	v_addc_co_u32_e32 v9, vcc, 0, v11, vcc
	v_lshl_add_u64 v[10:11], v[92:93], 0, s[64:65]
	global_load_dwordx4 v[28:31], v[8:9], off
	global_load_dwordx4 v[36:39], v[10:11], off
	v_add_co_u32_e32 v8, vcc, s46, v10
	s_or_b32 s38, s38, s22
	s_nop 0
	v_addc_co_u32_e32 v9, vcc, 0, v11, vcc
	v_lshl_add_u64 v[10:11], s[38:39], 1, v[94:95]
	global_load_dwordx4 v[52:55], v[8:9], off
	global_load_dwordx4 v[32:35], v[10:11], off
	v_lshl_add_u64 v[8:9], v[96:97], 0, s[58:59]
	global_load_dwordx4 v[8:11], v[8:9], off
	s_waitcnt lgkmcnt(0)
	s_mov_b32 s27, s11
	s_mov_b32 s25, s11
	s_waitcnt lgkmcnt(11)
	v_mfma_f32_16x16x32_bf16 v[182:185], v[182:185], v[72:75], 0
	s_waitcnt lgkmcnt(5)
	v_mfma_f32_16x16x32_bf16 v[72:75], v[206:209], v[72:75], 0
	s_waitcnt lgkmcnt(4)
	v_mfma_f32_16x16x32_bf16 v[72:75], v[210:213], v[114:117], v[72:75]
	s_waitcnt lgkmcnt(3)
; #define LDS_BAR() do { asm volatile("s_waitcnt lgkmcnt(0)" ::: "memory"); __builtin_amdgcn_s_barrier(); asm volatile("" ::: "memory"); } while (0)
; #define H2_LOADC(R, cc) do { const int c_ = (cc) < nch ? (cc) : nch - 1; \
;         h2_load<SAMP>(R, a, OF, SAMP ? MP + b * DEC_T : b * SEQ + c_ * 64, SAMP ? NB * 64 * GH + bh : (b * 64 + c_) * GH + h, h, es, tid, lane); } while (0)
; template <bool SAMP> __device__ __forceinline__ void g2_item(const Args& a, Frame& F, int bh, int es) {
;     ...
;     H2_LOADC(R0, 0); if (!SAMP) H2_LOADC(R1, 1);
;     LDS_BAR();
;     if (SAMP) { H2_STEP(R0, R2, 0, 0); }
;     else {
;         H2_STEP(R0, R2, 0, 0); H2_STEP(R1, R0, 1, 1);
;         for (int c = 2; c < 62; c += 6) { H2_STEP(R2, R1, c, 0); H2_STEP(R0, R2, c + 1, 1); H2_STEP(R1, R0, c + 2, 0); H2_STEP(R2, R1, c + 3, 1); H2_STEP(R0, R2, c + 4, 0); H2_STEP(R1, R0, c + 5, 1); }
	v_mfma_f32_16x16x32_bf16 v[72:75], v[214:217], v[118:121], v[72:75]
	s_waitcnt lgkmcnt(2)
	v_mfma_f32_16x16x32_bf16 v[72:75], v[218:221], v[170:173], v[72:75]
	s_waitcnt lgkmcnt(1)
	v_mfma_f32_16x16x32_bf16 v[72:75], v[222:225], v[174:177], v[72:75]
	s_waitcnt lgkmcnt(0)
	v_mfma_f32_16x16x32_bf16 v[72:75], v[226:229], v[178:181], v[72:75]
	v_mfma_f32_16x16x32_bf16 v[182:185], v[186:189], v[114:117], v[182:185]
	v_mfma_f32_16x16x32_bf16 v[114:117], v[190:193], v[118:121], v[182:185]
	v_add_u32_e32 v167, v141, v138
	ds_read_b128 v[118:121], v152
	s_nop 4
	ds_read_b128 v[182:185], v152 offset:64
	v_pk_mul_f32 v[66:67], v[66:67], v[62:63]
	v_mfma_f32_16x16x32_bf16 v[114:117], v[194:197], v[170:173], v[114:117]
	ds_read_b128 v[170:173], v167
	ds_read_b128 v[186:189], v167 offset:64
	ds_read_b128 v[190:193], v167 offset:2560
	ds_read_b128 v[194:197], v167 offset:2624
	v_pk_mul_f32 v[64:65], v[64:65], v[60:61]
	v_pk_mul_f32 v[70:71], v[70:71], v[62:63]
	v_mfma_f32_16x16x32_bf16 v[114:117], v[198:201], v[174:177], v[114:117]
	ds_read_b128 v[174:177], v167 offset:5120
	ds_read_b128 v[198:201], v167 offset:5184
	ds_read_b128 v[206:209], v167 offset:7680
	ds_read_b128 v[210:213], v167 offset:7744
	s_waitcnt lgkmcnt(0)
	v_pk_mul_f32 v[68:69], v[68:69], v[60:61]
	v_mfma_f32_16x16x32_bf16 v[114:117], v[202:205], v[178:181], v[114:117]
	v_mul_f32_e64 v78, v78, v62
	v_mul_f32_e64 v79, v79, v63
	v_pk_mul_f32 v[76:77], v[76:77], v[60:61]
	v_pk_mul_f32 v[62:63], v[112:113], v[62:63]
	v_pk_mul_f32 v[60:61], v[110:111], v[60:61]
	v_lshl_add_u64 v[112:113], v[98:99], 0, s[36:37]
	v_cvt_pk_bf16_f32 v72, v72, v73
	v_cvt_pk_bf16_f32 v73, v74, v75
	s_waitcnt lgkmcnt(7)
	v_mfma_f32_16x16x32_bf16 v[64:67], v[118:121], v[170:173], v[64:67]
	global_store_dwordx2 v[112:113], v[72:73], off offset:32
	s_lshl_b64 s[36:37], s[28:29], 11
	s_lshl_b32 s29, s56, 9
	s_waitcnt lgkmcnt(5)
	v_mfma_f32_16x16x32_bf16 v[68:71], v[118:121], v[190:193], v[68:71]
	s_or_b32 s21, s21, s29
	v_cvt_pk_bf16_f32 v110, v114, v115
	v_cvt_pk_bf16_f32 v111, v116, v117
	s_waitcnt lgkmcnt(3)
	v_mfma_f32_16x16x32_bf16 v[76:79], v[118:121], v[174:177], v[76:79]
	s_or_b32 s38, s36, s21
	s_mov_b32 s39, s37
	s_or_b32 s36, s36, s26
	s_waitcnt lgkmcnt(1)
	v_mfma_f32_16x16x32_bf16 v[72:75], v[118:121], v[206:209], v[60:63]
	s_or_b32 s34, s34, s10
	global_store_dwordx2 v[112:113], v[110:111], off
	v_lshl_add_u64 v[110:111], s[38:39], 0, v[84:85]
	v_mfma_f32_16x16x32_bf16 v[64:67], v[182:185], v[186:189], v[64:67]
	v_lshl_add_u64 v[112:113], s[36:37], 0, v[80:81]
	v_lshl_add_u64 v[114:115], s[34:35], 0, v[82:83]
	s_or_b32 s30, s30, 36
	v_mfma_f32_16x16x32_bf16 v[60:63], v[182:185], v[194:197], v[68:71]
	v_lshl_add_u64 v[116:117], s[38:39], 0, v[106:107]
	s_mov_b32 s21, -4
	v_mfma_f32_16x16x32_bf16 v[68:71], v[182:185], v[198:201], v[76:79]
	s_waitcnt lgkmcnt(0)
	v_mfma_f32_16x16x32_bf16 v[72:75], v[182:185], v[210:213], v[72:75]
.LBB0_1356:
	s_waitcnt vmcnt(11)
	ds_write_b128 v143, v[20:23]
	ds_write_b128 v154, v[24:27] offset:10240
	ds_write_b128 v155, v[44:47] offset:28672
	ds_write_b128 v156, v[40:43] offset:10240
	ds_write_b128 v157, v[56:59] offset:28672
	ds_write_b16 v153, v48 offset:49152
	ds_write_b16_d16_hi v153, v48 offset:49312
	ds_write_b16 v153, v49 offset:49472
	ds_write_b16_d16_hi v153, v49 offset:49632
	ds_write_b16 v153, v50 offset:49792
	ds_write_b16_d16_hi v153, v50 offset:49952
	ds_write_b16 v153, v51 offset:50112
	ds_write_b16_d16_hi v153, v51 offset:50272
	v_cvt_pk_bf16_f32 v20, v64, v65
	v_cvt_pk_bf16_f32 v21, v66, v67
	v_cvt_pk_bf16_f32 v22, v60, v61
	v_cvt_pk_bf16_f32 v23, v62, v63
	ds_write2st64_b64 v158, v[20:21], v[22:23] offset0:116 offset1:125
	v_cvt_pk_bf16_f32 v20, v68, v69
	v_cvt_pk_bf16_f32 v21, v70, v71
	v_cvt_pk_bf16_f32 v22, v72, v73
	v_cvt_pk_bf16_f32 v23, v74, v75
	v_lshl_add_u64 v[120:121], s[96:97], 0, v[114:115]
	s_mov_b32 s29, 0x1cf80000
	ds_write2st64_b64 v144, v[20:21], v[22:23] offset0:116 offset1:125
	v_add_co_u32_e32 v20, vcc, s29, v120
	v_lshl_add_u64 v[118:119], s[96:97], 0, v[112:113]
	s_nop 0
	v_addc_co_u32_e32 v21, vcc, 0, v121, vcc
	s_mov_b32 s29, 0x7d40000
	s_sub_i32 s34, s30, 20
	v_add_co_u32_e32 v22, vcc, s29, v118
	s_waitcnt lgkmcnt(0)
	s_barrier
	ds_read_b128 v[170:173], v166
	ds_read_b128 v[174:177], v166 offset:64
	ds_read_b128 v[178:181], v145 offset:10240
	ds_read_b128 v[182:185], v145 offset:10304
	ds_read_b128 v[186:189], v145 offset:10368
	ds_read_b128 v[190:193], v145 offset:10432
	ds_read_b128 v[194:197], v160 offset:49152
	ds_read_b128 v[198:201], v160 offset:49216
	ds_read_b128 v[202:205], v159 offset:59392
	ds_read_b128 v[206:209], v159 offset:59456
	ds_read_b128 v[210:213], v159 offset:59520
	ds_read_b128 v[214:217], v159 offset:59584
	ds_read_b128 v[218:221], v160 offset:51712
	ds_read_b128 v[222:225], v160 offset:51776
	ds_read_b128 v[226:229], v159 offset:64000
	ds_read_b128 v[230:233], v159 offset:64064
	ds_read_b128 v[234:237], v159 offset:64128
	ds_read_b128 v[238:241], v159 offset:64192
	s_ashr_i32 s35, s34, 31
	v_addc_co_u32_e32 v23, vcc, 0, v119, vcc
	s_mov_b32 s29, 0x7d50000
	s_lshl_b64 s[36:37], s[34:35], 14
	global_load_dwordx4 v[24:27], v[20:21], off
	global_load_dwordx4 v[40:43], v[22:23], off
	v_add_co_u32_e32 v20, vcc, s29, v118
	v_lshl_add_u64 v[22:23], v[92:93], 0, s[36:37]
	s_nop 0
	v_addc_co_u32_e32 v21, vcc, 0, v119, vcc
	global_load_dwordx4 v[44:47], v[20:21], off
	global_load_dwordx4 v[56:59], v[22:23], off
	v_add_co_u32_e32 v20, vcc, s46, v22
	v_lshl_add_u64 v[122:123], s[96:97], 0, v[110:111]
	s_nop 0
	v_addc_co_u32_e32 v21, vcc, 0, v23, vcc
	s_lshl_b64 s[34:35], s[34:35], 9
	v_add_co_u32_e32 v22, vcc, s47, v122
	s_nop 1
	v_addc_co_u32_e32 v23, vcc, 0, v123, vcc
	global_load_dwordx4 v[76:79], v[20:21], off
	global_load_dwordx4 v[48:51], v[22:23], off
	v_lshl_add_u64 v[20:21], v[96:97], 0, s[34:35]
	global_load_dwordx4 v[20:23], v[20:21], off
	s_waitcnt lgkmcnt(0)
	s_waitcnt lgkmcnt(11)
	v_mfma_f32_16x16x32_bf16 v[194:197], v[194:197], v[170:173], 0
	s_waitcnt lgkmcnt(5)
	v_mfma_f32_16x16x32_bf16 v[170:173], v[218:221], v[170:173], 0
	s_waitcnt lgkmcnt(4)
	v_mfma_f32_16x16x32_bf16 v[170:173], v[222:225], v[174:177], v[170:173]
	s_waitcnt lgkmcnt(3)
	v_mfma_f32_16x16x32_bf16 v[170:173], v[226:229], v[178:181], v[170:173]
	s_waitcnt lgkmcnt(2)
	v_mfma_f32_16x16x32_bf16 v[170:173], v[230:233], v[182:185], v[170:173]
	s_waitcnt lgkmcnt(1)
	v_mfma_f32_16x16x32_bf16 v[170:173], v[234:237], v[186:189], v[170:173]
	v_mfma_f32_16x16x32_bf16 v[194:197], v[198:201], v[174:177], v[194:197]
	s_waitcnt lgkmcnt(0)
	v_mfma_f32_16x16x32_bf16 v[170:173], v[238:241], v[190:193], v[170:173]
	v_mfma_f32_16x16x32_bf16 v[174:177], v[202:205], v[178:181], v[194:197]
	ds_read_b128 v[178:181], v146 offset:28672
	s_nop 3
	ds_read_b128 v[194:197], v146 offset:28736
	ds_read_b128 v[198:201], v161 offset:49152
	ds_read_b128 v[202:205], v161 offset:49216
	v_pk_mul_f32 v[66:67], v[66:67], v[6:7]
	v_pk_mul_f32 v[64:65], v[64:65], v[4:5]
	v_mfma_f32_16x16x32_bf16 v[174:177], v[206:209], v[182:185], v[174:177]
	ds_read_b128 v[182:185], v161 offset:51712
	ds_read_b128 v[206:209], v161 offset:51776
	ds_read_b128 v[218:221], v161 offset:54272
	ds_read_b128 v[222:225], v161 offset:54336
	v_pk_mul_f32 v[62:63], v[62:63], v[6:7]
	v_pk_mul_f32 v[60:61], v[60:61], v[4:5]
	v_mfma_f32_16x16x32_bf16 v[174:177], v[210:213], v[186:189], v[174:177]
	ds_read_b128 v[186:189], v161 offset:56832
	ds_read_b128 v[210:213], v161 offset:56896
	s_waitcnt lgkmcnt(0)
	v_mfma_f32_16x16x32_bf16 v[174:177], v[214:217], v[190:193], v[174:177]
	v_mul_f32_e64 v192, v70, v6
	v_mul_f32_e64 v193, v71, v7
	v_pk_mul_f32 v[190:191], v[68:69], v[4:5]
	v_pk_mul_f32 v[6:7], v[74:75], v[6:7]
	v_pk_mul_f32 v[4:5], v[72:73], v[4:5]
	v_lshl_add_u64 v[68:69], s[96:97], 0, v[116:117]
	s_mov_b32 s29, 0xbd80000
	v_add_co_u32_e32 v74, vcc, s29, v68
	v_cvt_pk_bf16_f32 v70, v174, v175
	s_waitcnt lgkmcnt(7)
	v_mfma_f32_16x16x32_bf16 v[64:67], v[178:181], v[198:201], v[64:67]
	v_cvt_pk_bf16_f32 v71, v176, v177
	v_addc_co_u32_e32 v75, vcc, 0, v69, vcc
	s_waitcnt lgkmcnt(5)
	v_mfma_f32_16x16x32_bf16 v[60:63], v[178:181], v[182:185], v[60:63]
	global_store_dwordx2 v[74:75], v[70:71], off
	v_cvt_pk_bf16_f32 v170, v170, v171
	v_cvt_pk_bf16_f32 v171, v172, v173
	s_waitcnt lgkmcnt(3)
	v_mfma_f32_16x16x32_bf16 v[70:73], v[178:181], v[218:221], v[190:193]
	global_store_dwordx2 v[74:75], v[170:171], off offset:32
	s_waitcnt vmcnt(11)
	ds_write_b128 v147, v[12:15]
	ds_write_b128 v162, v[16:19]
	s_waitcnt lgkmcnt(3)
	v_mfma_f32_16x16x32_bf16 v[4:7], v[178:181], v[186:189], v[4:7]
	ds_write_b128 v163, v[36:39]
	ds_write_b128 v164, v[28:31]
	ds_write_b128 v165, v[52:55]
	ds_write_b16 v3, v32
	ds_write_b16_d16_hi v3, v32 offset:160
	ds_write_b16 v3, v33 offset:320
	ds_write_b16_d16_hi v3, v33 offset:480
	ds_write_b16 v3, v34 offset:640
	ds_write_b16_d16_hi v3, v34 offset:800
	v_mfma_f32_16x16x32_bf16 v[64:67], v[194:197], v[202:205], v[64:67]
	ds_write_b16 v3, v35 offset:960
	ds_write_b16_d16_hi v3, v35 offset:1120
	s_mov_b32 s29, 0x1cf88000
	s_add_i32 s34, s30, -16
	v_mfma_f32_16x16x32_bf16 v[28:31], v[194:197], v[206:209], v[60:63]
	s_ashr_i32 s35, s34, 31
	s_lshl_b64 s[36:37], s[34:35], 14
	s_lshl_b64 s[34:35], s[34:35], 9
	v_mfma_f32_16x16x32_bf16 v[70:73], v[194:197], v[222:225], v[70:73]
	s_waitcnt lgkmcnt(13)
	v_mfma_f32_16x16x32_bf16 v[170:173], v[194:197], v[210:213], v[4:7]
	s_nop 2
	v_cvt_pk_bf16_f32 v4, v64, v65
	v_cvt_pk_bf16_f32 v5, v66, v67
	v_cvt_pk_bf16_f32 v6, v28, v29
	v_cvt_pk_bf16_f32 v7, v30, v31
	ds_write2st64_b64 v148, v[4:5], v[6:7] offset1:9
	v_cvt_pk_bf16_f32 v4, v70, v71
	v_cvt_pk_bf16_f32 v5, v72, v73
	v_cvt_pk_bf16_f32 v6, v170, v171
	v_cvt_pk_bf16_f32 v7, v172, v173
	ds_write2st64_b64 v148, v[4:5], v[6:7] offset0:18 offset1:27
	v_add_co_u32_e32 v4, vcc, s29, v120
	s_mov_b32 s29, 0x7d60000
	s_nop 0
	v_addc_co_u32_e32 v5, vcc, 0, v121, vcc
	v_add_co_u32_e32 v6, vcc, s29, v118
	s_waitcnt lgkmcnt(0)
	s_barrier
	ds_read_b128 v[174:177], v149
	ds_read_b128 v[178:181], v149 offset:64
	ds_read_b128 v[182:185], v150
	ds_read_b128 v[186:189], v150 offset:64
	ds_read_b128 v[190:193], v150 offset:128
	ds_read_b128 v[194:197], v150 offset:192
	ds_read_b128 v[198:201], v168
	ds_read_b128 v[202:205], v168 offset:64
	ds_read_b128 v[206:209], v151
	ds_read_b128 v[210:213], v151 offset:64
	ds_read_b128 v[214:217], v151 offset:128
	ds_read_b128 v[218:221], v151 offset:192
	ds_read_b128 v[222:225], v168 offset:2560
	ds_read_b128 v[226:229], v168 offset:2624
	ds_read_b128 v[230:233], v151 offset:4608
	ds_read_b128 v[234:237], v151 offset:4672
	ds_read_b128 v[238:241], v151 offset:4736
	ds_read_b128 v[242:245], v151 offset:4800
	s_nop 0
	v_addc_co_u32_e32 v7, vcc, 0, v119, vcc
	s_mov_b32 s29, 0x7d70000
	global_load_dwordx4 v[12:15], v[4:5], off
	global_load_dwordx4 v[16:19], v[6:7], off
	v_add_co_u32_e32 v4, vcc, s29, v118
	v_lshl_add_u64 v[6:7], v[92:93], 0, s[36:37]
	s_nop 0
	v_addc_co_u32_e32 v5, vcc, 0, v119, vcc
	global_load_dwordx4 v[32:35], v[4:5], off
	global_load_dwordx4 v[52:55], v[6:7], off
	v_add_co_u32_e32 v4, vcc, s46, v6
	s_nop 1
	v_addc_co_u32_e32 v5, vcc, 0, v7, vcc
	v_add_co_u32_e32 v6, vcc, s48, v122
	s_nop 1
	v_addc_co_u32_e32 v7, vcc, 0, v123, vcc
	global_load_dwordx4 v[60:63], v[4:5], off
	global_load_dwordx4 v[36:39], v[6:7], off
	v_lshl_add_u64 v[4:5], v[96:97], 0, s[34:35]
	global_load_dwordx4 v[4:7], v[4:5], off
	s_waitcnt lgkmcnt(0)
	s_waitcnt lgkmcnt(11)
	v_mfma_f32_16x16x32_bf16 v[198:201], v[198:201], v[174:177], 0
	s_waitcnt lgkmcnt(5)
	v_mfma_f32_16x16x32_bf16 v[174:177], v[222:225], v[174:177], 0
	s_waitcnt lgkmcnt(4)
	v_mfma_f32_16x16x32_bf16 v[174:177], v[226:229], v[178:181], v[174:177]
	s_waitcnt lgkmcnt(3)
	v_mfma_f32_16x16x32_bf16 v[174:177], v[230:233], v[182:185], v[174:177]
	s_waitcnt lgkmcnt(2)
	v_mfma_f32_16x16x32_bf16 v[174:177], v[234:237], v[186:189], v[174:177]
	s_waitcnt lgkmcnt(1)
	v_mfma_f32_16x16x32_bf16 v[174:177], v[238:241], v[190:193], v[174:177]
	v_mfma_f32_16x16x32_bf16 v[198:201], v[202:205], v[178:181], v[198:201]
	s_waitcnt lgkmcnt(0)
	v_mfma_f32_16x16x32_bf16 v[174:177], v[242:245], v[194:197], v[174:177]
	v_mfma_f32_16x16x32_bf16 v[178:181], v[206:209], v[182:185], v[198:201]
	ds_read_b128 v[182:185], v152
	s_nop 3
	ds_read_b128 v[198:201], v152 offset:64
	ds_read_b128 v[202:205], v167
	ds_read_b128 v[206:209], v167 offset:64
	v_pk_mul_f32 v[66:67], v[66:67], v[10:11]
	v_pk_mul_f32 v[64:65], v[64:65], v[8:9]
	v_mfma_f32_16x16x32_bf16 v[178:181], v[210:213], v[186:189], v[178:181]
	ds_read_b128 v[186:189], v167 offset:2560
	ds_read_b128 v[210:213], v167 offset:2624
	ds_read_b128 v[222:225], v167 offset:5120
	ds_read_b128 v[226:229], v167 offset:5184
	v_pk_mul_f32 v[30:31], v[30:31], v[10:11]
	v_pk_mul_f32 v[28:29], v[28:29], v[8:9]
	v_mfma_f32_16x16x32_bf16 v[178:181], v[214:217], v[190:193], v[178:181]
	ds_read_b128 v[190:193], v167 offset:7680
	ds_read_b128 v[214:217], v167 offset:7744
	s_waitcnt lgkmcnt(0)
	v_pk_mul_f32 v[72:73], v[72:73], v[10:11]
	v_pk_mul_f32 v[70:71], v[70:71], v[8:9]
	v_pk_mul_f32 v[10:11], v[172:173], v[10:11]
	v_pk_mul_f32 v[8:9], v[170:171], v[8:9]
	v_mfma_f32_16x16x32_bf16 v[178:181], v[218:221], v[194:197], v[178:181]
	s_mov_b32 s29, 0xbda0000
	s_waitcnt lgkmcnt(7)
	v_mfma_f32_16x16x32_bf16 v[64:67], v[182:185], v[202:205], v[64:67]
	v_add_co_u32_e32 v170, vcc, s29, v68
	s_nop 3
	v_cvt_pk_bf16_f32 v74, v178, v179
	s_waitcnt lgkmcnt(5)
	v_mfma_f32_16x16x32_bf16 v[28:31], v[182:185], v[186:189], v[28:31]
	v_cvt_pk_bf16_f32 v75, v180, v181
	v_addc_co_u32_e32 v171, vcc, 0, v69, vcc
	s_waitcnt lgkmcnt(3)
	v_mfma_f32_16x16x32_bf16 v[70:73], v[182:185], v[222:225], v[70:73]
	global_store_dwordx2 v[170:171], v[74:75], off
	v_cvt_pk_bf16_f32 v74, v174, v175
	v_cvt_pk_bf16_f32 v75, v176, v177
	s_waitcnt lgkmcnt(1)
	v_mfma_f32_16x16x32_bf16 v[8:11], v[182:185], v[190:193], v[8:11]
	global_store_dwordx2 v[170:171], v[74:75], off offset:32
	s_waitcnt vmcnt(11)
	ds_write_b128 v143, v[24:27]
	ds_write_b128 v154, v[40:43] offset:10240
	ds_write_b128 v155, v[56:59] offset:28672
	v_mfma_f32_16x16x32_bf16 v[64:67], v[198:201], v[206:209], v[64:67]
	ds_write_b128 v156, v[44:47] offset:10240
	ds_write_b128 v157, v[76:79] offset:28672
	ds_write_b16 v153, v48 offset:49152
	ds_write_b16_d16_hi v153, v48 offset:49312
	ds_write_b16 v153, v49 offset:49472
	ds_write_b16_d16_hi v153, v49 offset:49632
	ds_write_b16 v153, v50 offset:49792
	ds_write_b16_d16_hi v153, v50 offset:49952
	ds_write_b16 v153, v51 offset:50112
	v_mfma_f32_16x16x32_bf16 v[74:77], v[198:201], v[210:213], v[28:31]
	ds_write_b16_d16_hi v153, v51 offset:50272
	s_mov_b32 s29, 0x1cf90000
	s_add_i32 s34, s30, -12
	v_mfma_f32_16x16x32_bf16 v[70:73], v[198:201], v[226:229], v[70:73]
	s_ashr_i32 s35, s34, 31
	s_lshl_b64 s[36:37], s[34:35], 14
	s_lshl_b64 s[34:35], s[34:35], 9
	s_waitcnt lgkmcnt(13)
	v_mfma_f32_16x16x32_bf16 v[170:173], v[198:201], v[214:217], v[8:11]
	s_nop 2
	v_cvt_pk_bf16_f32 v8, v64, v65
	v_cvt_pk_bf16_f32 v9, v66, v67
	v_cvt_pk_bf16_f32 v10, v74, v75
	v_cvt_pk_bf16_f32 v11, v76, v77
	ds_write2st64_b64 v158, v[8:9], v[10:11] offset0:116 offset1:125
	v_cvt_pk_bf16_f32 v8, v70, v71
	v_cvt_pk_bf16_f32 v9, v72, v73
	v_cvt_pk_bf16_f32 v10, v170, v171
	v_cvt_pk_bf16_f32 v11, v172, v173
	ds_write2st64_b64 v144, v[8:9], v[10:11] offset0:116 offset1:125
	v_add_co_u32_e32 v8, vcc, s29, v120
	s_mov_b32 s29, 0x7d80000
	s_nop 0
	v_addc_co_u32_e32 v9, vcc, 0, v121, vcc
	v_add_co_u32_e32 v10, vcc, s29, v118
	s_waitcnt lgkmcnt(0)
	s_barrier
	ds_read_b128 v[174:177], v166
	ds_read_b128 v[178:181], v166 offset:64
	ds_read_b128 v[182:185], v145 offset:10240
	ds_read_b128 v[186:189], v145 offset:10304
	ds_read_b128 v[190:193], v145 offset:10368
	ds_read_b128 v[194:197], v145 offset:10432
	ds_read_b128 v[198:201], v160 offset:49152
	ds_read_b128 v[202:205], v160 offset:49216
	ds_read_b128 v[206:209], v159 offset:59392
	ds_read_b128 v[210:213], v159 offset:59456
	ds_read_b128 v[214:217], v159 offset:59520
	ds_read_b128 v[218:221], v159 offset:59584
	ds_read_b128 v[222:225], v160 offset:51712
	ds_read_b128 v[226:229], v160 offset:51776
	ds_read_b128 v[230:233], v159 offset:64000
	ds_read_b128 v[234:237], v159 offset:64064
	ds_read_b128 v[238:241], v159 offset:64128
	ds_read_b128 v[242:245], v159 offset:64192
	s_nop 0
	v_addc_co_u32_e32 v11, vcc, 0, v119, vcc
	s_mov_b32 s29, 0x7d90000
	global_load_dwordx4 v[24:27], v[8:9], off
	global_load_dwordx4 v[28:31], v[10:11], off
	v_add_co_u32_e32 v8, vcc, s29, v118
	v_lshl_add_u64 v[10:11], v[92:93], 0, s[36:37]
	s_nop 0
	v_addc_co_u32_e32 v9, vcc, 0, v119, vcc
	global_load_dwordx4 v[40:43], v[8:9], off
	global_load_dwordx4 v[48:51], v[10:11], off
	v_add_co_u32_e32 v8, vcc, s46, v10
	s_nop 1
	v_addc_co_u32_e32 v9, vcc, 0, v11, vcc
	v_add_co_u32_e32 v10, vcc, s49, v122
	s_nop 1
	v_addc_co_u32_e32 v11, vcc, 0, v123, vcc
	global_load_dwordx4 v[56:59], v[8:9], off
	global_load_dwordx4 v[44:47], v[10:11], off
	v_lshl_add_u64 v[8:9], v[96:97], 0, s[34:35]
	global_load_dwordx4 v[8:11], v[8:9], off
	s_waitcnt lgkmcnt(0)
	s_waitcnt lgkmcnt(11)
	v_mfma_f32_16x16x32_bf16 v[198:201], v[198:201], v[174:177], 0
	s_waitcnt lgkmcnt(5)
	v_mfma_f32_16x16x32_bf16 v[174:177], v[222:225], v[174:177], 0
	s_waitcnt lgkmcnt(4)
	v_mfma_f32_16x16x32_bf16 v[174:177], v[226:229], v[178:181], v[174:177]
	s_waitcnt lgkmcnt(3)
	v_mfma_f32_16x16x32_bf16 v[174:177], v[230:233], v[182:185], v[174:177]
	s_waitcnt lgkmcnt(2)
	v_mfma_f32_16x16x32_bf16 v[174:177], v[234:237], v[186:189], v[174:177]
	s_waitcnt lgkmcnt(1)
	v_mfma_f32_16x16x32_bf16 v[174:177], v[238:241], v[190:193], v[174:177]
	v_mfma_f32_16x16x32_bf16 v[198:201], v[202:205], v[178:181], v[198:201]
	s_waitcnt lgkmcnt(0)
	v_mfma_f32_16x16x32_bf16 v[174:177], v[242:245], v[194:197], v[174:177]
	v_mfma_f32_16x16x32_bf16 v[178:181], v[206:209], v[182:185], v[198:201]
	ds_read_b128 v[182:185], v146 offset:28672
	s_nop 3
	ds_read_b128 v[198:201], v146 offset:28736
	ds_read_b128 v[202:205], v161 offset:49152
	ds_read_b128 v[206:209], v161 offset:49216
	v_pk_mul_f32 v[66:67], v[66:67], v[22:23]
	v_pk_mul_f32 v[64:65], v[64:65], v[20:21]
	v_mfma_f32_16x16x32_bf16 v[178:181], v[210:213], v[186:189], v[178:181]
	ds_read_b128 v[186:189], v161 offset:51712
	ds_read_b128 v[210:213], v161 offset:51776
	ds_read_b128 v[222:225], v161 offset:54272
	ds_read_b128 v[226:229], v161 offset:54336
	v_pk_mul_f32 v[76:77], v[76:77], v[22:23]
	v_pk_mul_f32 v[74:75], v[74:75], v[20:21]
	v_mfma_f32_16x16x32_bf16 v[178:181], v[214:217], v[190:193], v[178:181]
	ds_read_b128 v[190:193], v161 offset:56832
	ds_read_b128 v[214:217], v161 offset:56896
	s_waitcnt lgkmcnt(0)
	v_pk_mul_f32 v[72:73], v[72:73], v[22:23]
	v_pk_mul_f32 v[70:71], v[70:71], v[20:21]
	v_pk_mul_f32 v[22:23], v[172:173], v[22:23]
	v_pk_mul_f32 v[20:21], v[170:171], v[20:21]
	v_mfma_f32_16x16x32_bf16 v[178:181], v[218:221], v[194:197], v[178:181]
	s_waitcnt lgkmcnt(7)
	v_mfma_f32_16x16x32_bf16 v[64:67], v[182:185], v[202:205], v[64:67]
	v_add_co_u32_e32 v170, vcc, s47, v68
	s_nop 4
	v_cvt_pk_bf16_f32 v78, v178, v179
	s_waitcnt lgkmcnt(5)
	v_mfma_f32_16x16x32_bf16 v[74:77], v[182:185], v[186:189], v[74:77]
	v_cvt_pk_bf16_f32 v79, v180, v181
	v_addc_co_u32_e32 v171, vcc, 0, v69, vcc
	s_waitcnt lgkmcnt(3)
	v_mfma_f32_16x16x32_bf16 v[70:73], v[182:185], v[222:225], v[70:73]
	global_store_dwordx2 v[170:171], v[78:79], off
	v_cvt_pk_bf16_f32 v78, v174, v175
	v_cvt_pk_bf16_f32 v79, v176, v177
	s_waitcnt lgkmcnt(1)
	v_mfma_f32_16x16x32_bf16 v[20:23], v[182:185], v[190:193], v[20:23]
	global_store_dwordx2 v[170:171], v[78:79], off offset:32
	s_waitcnt vmcnt(11)
	ds_write_b128 v147, v[12:15]
	ds_write_b128 v162, v[16:19]
	ds_write_b128 v163, v[52:55]
	v_mfma_f32_16x16x32_bf16 v[170:173], v[198:201], v[206:209], v[64:67]
	ds_write_b128 v164, v[32:35]
	ds_write_b128 v165, v[60:63]
	ds_write_b16 v3, v36
	ds_write_b16_d16_hi v3, v36 offset:160
	ds_write_b16 v3, v37 offset:320
	ds_write_b16_d16_hi v3, v37 offset:480
	ds_write_b16 v3, v38 offset:640
	ds_write_b16_d16_hi v3, v38 offset:800
	ds_write_b16 v3, v39 offset:960
	v_mfma_f32_16x16x32_bf16 v[74:77], v[198:201], v[210:213], v[74:77]
	v_cvt_pk_bf16_f32 v12, v170, v171
	v_cvt_pk_bf16_f32 v13, v172, v173
	ds_write_b16_d16_hi v3, v39 offset:1120
	v_mfma_f32_16x16x32_bf16 v[70:73], v[198:201], v[226:229], v[70:73]
	s_mov_b32 s29, 0x1cf98000
	s_nop 2
	v_cvt_pk_bf16_f32 v14, v74, v75
	v_cvt_pk_bf16_f32 v15, v76, v77
	s_waitcnt lgkmcnt(13)
	v_mfma_f32_16x16x32_bf16 v[20:23], v[198:201], v[214:217], v[20:23]
	ds_write2st64_b64 v148, v[12:13], v[14:15] offset1:9
	v_cvt_pk_bf16_f32 v12, v70, v71
	v_cvt_pk_bf16_f32 v13, v72, v73
	s_add_i32 s34, s30, -8
	s_ashr_i32 s35, s34, 31
	s_nop 2
	v_cvt_pk_bf16_f32 v14, v20, v21
	v_cvt_pk_bf16_f32 v15, v22, v23
	ds_write2st64_b64 v148, v[12:13], v[14:15] offset0:18 offset1:27
	v_add_co_u32_e32 v12, vcc, s29, v120
	s_mov_b32 s29, 0x7da0000
	s_nop 0
	v_addc_co_u32_e32 v13, vcc, 0, v121, vcc
	v_add_co_u32_e32 v16, vcc, s29, v118
	s_mov_b32 s29, 0x7db0000
	s_nop 0
	v_addc_co_u32_e32 v17, vcc, 0, v119, vcc
	s_lshl_b64 s[36:37], s[34:35], 14
	v_add_co_u32_e32 v32, vcc, s29, v118
	s_waitcnt lgkmcnt(0)
	s_barrier
	ds_read_b128 v[174:177], v149
	ds_read_b128 v[178:181], v149 offset:64
	ds_read_b128 v[182:185], v150
	ds_read_b128 v[186:189], v150 offset:64
	ds_read_b128 v[190:193], v150 offset:128
	ds_read_b128 v[194:197], v150 offset:192
	ds_read_b128 v[198:201], v168
	ds_read_b128 v[202:205], v168 offset:64
	ds_read_b128 v[206:209], v151
	ds_read_b128 v[210:213], v151 offset:64
	ds_read_b128 v[214:217], v151 offset:128
	ds_read_b128 v[218:221], v151 offset:192
	ds_read_b128 v[222:225], v168 offset:2560
	ds_read_b128 v[226:229], v168 offset:2624
	ds_read_b128 v[230:233], v151 offset:4608
	ds_read_b128 v[234:237], v151 offset:4672
	ds_read_b128 v[238:241], v151 offset:4736
	ds_read_b128 v[242:245], v151 offset:4800
	s_nop 0
	v_addc_co_u32_e32 v33, vcc, 0, v119, vcc
	v_lshl_add_u64 v[36:37], v[92:93], 0, s[36:37]
	global_load_dwordx4 v[12:15], v[12:13], off
	s_nop 0
	global_load_dwordx4 v[16:19], v[16:17], off
	s_nop 0
	global_load_dwordx4 v[32:35], v[32:33], off
	s_nop 0
	global_load_dwordx4 v[52:55], v[36:37], off
	v_add_co_u32_e32 v36, vcc, s46, v36
	s_lshl_b64 s[34:35], s[34:35], 9
	s_nop 0
	v_addc_co_u32_e32 v37, vcc, 0, v37, vcc
	v_add_co_u32_e32 v38, vcc, s50, v122
	v_lshl_add_u64 v[60:61], v[96:97], 0, s[34:35]
	s_nop 0
	v_addc_co_u32_e32 v39, vcc, 0, v123, vcc
	global_load_dwordx4 v[64:67], v[36:37], off
	s_nop 0
	global_load_dwordx4 v[36:39], v[38:39], off
	s_nop 0
	global_load_dwordx4 v[60:63], v[60:61], off
	s_waitcnt lgkmcnt(0)
	s_waitcnt lgkmcnt(11)
	v_mfma_f32_16x16x32_bf16 v[198:201], v[198:201], v[174:177], 0
	s_waitcnt lgkmcnt(5)
	v_mfma_f32_16x16x32_bf16 v[174:177], v[222:225], v[174:177], 0
	s_waitcnt lgkmcnt(4)
	v_mfma_f32_16x16x32_bf16 v[174:177], v[226:229], v[178:181], v[174:177]
	s_waitcnt lgkmcnt(3)
	v_mfma_f32_16x16x32_bf16 v[174:177], v[230:233], v[182:185], v[174:177]
	s_waitcnt lgkmcnt(2)
	v_mfma_f32_16x16x32_bf16 v[174:177], v[234:237], v[186:189], v[174:177]
	s_waitcnt lgkmcnt(1)
	v_mfma_f32_16x16x32_bf16 v[174:177], v[238:241], v[190:193], v[174:177]
	v_mfma_f32_16x16x32_bf16 v[198:201], v[202:205], v[178:181], v[198:201]
	s_waitcnt lgkmcnt(0)
	v_mfma_f32_16x16x32_bf16 v[174:177], v[242:245], v[194:197], v[174:177]
	v_mfma_f32_16x16x32_bf16 v[178:181], v[206:209], v[182:185], v[198:201]
	ds_read_b128 v[182:185], v152
	s_nop 3
	ds_read_b128 v[198:201], v152 offset:64
	ds_read_b128 v[202:205], v167
	ds_read_b128 v[206:209], v167 offset:64
	v_pk_mul_f32 v[172:173], v[172:173], v[6:7]
	v_pk_mul_f32 v[170:171], v[170:171], v[4:5]
	v_mfma_f32_16x16x32_bf16 v[178:181], v[210:213], v[186:189], v[178:181]
	ds_read_b128 v[186:189], v167 offset:2560
	ds_read_b128 v[210:213], v167 offset:2624
	ds_read_b128 v[222:225], v167 offset:5120
	ds_read_b128 v[226:229], v167 offset:5184
	v_pk_mul_f32 v[76:77], v[76:77], v[6:7]
	v_pk_mul_f32 v[74:75], v[74:75], v[4:5]
	v_mfma_f32_16x16x32_bf16 v[178:181], v[214:217], v[190:193], v[178:181]
	ds_read_b128 v[190:193], v167 offset:7680
	ds_read_b128 v[214:217], v167 offset:7744
	s_waitcnt lgkmcnt(0)
	v_pk_mul_f32 v[72:73], v[72:73], v[6:7]
	v_pk_mul_f32 v[70:71], v[70:71], v[4:5]
	v_pk_mul_f32 v[6:7], v[22:23], v[6:7]
	v_pk_mul_f32 v[4:5], v[20:21], v[4:5]
	v_mfma_f32_16x16x32_bf16 v[178:181], v[218:221], v[194:197], v[178:181]
	s_waitcnt lgkmcnt(7)
	v_mfma_f32_16x16x32_bf16 v[20:23], v[182:185], v[202:205], v[170:173]
	s_nop 5
	v_cvt_pk_bf16_f32 v78, v178, v179
	v_cvt_pk_bf16_f32 v79, v180, v181
	s_mov_b32 s29, 0x1cfa0000
	s_waitcnt lgkmcnt(5)
	v_mfma_f32_16x16x32_bf16 v[74:77], v[182:185], v[186:189], v[74:77]
	v_add_co_u32_e32 v170, vcc, s48, v68
	s_add_i32 s34, s30, -4
	s_nop 0
	v_addc_co_u32_e32 v171, vcc, 0, v69, vcc
	s_waitcnt lgkmcnt(3)
	v_mfma_f32_16x16x32_bf16 v[70:73], v[182:185], v[222:225], v[70:73]
	global_store_dwordx2 v[170:171], v[78:79], off
	v_cvt_pk_bf16_f32 v78, v174, v175
	v_cvt_pk_bf16_f32 v79, v176, v177
	s_waitcnt lgkmcnt(1)
	v_mfma_f32_16x16x32_bf16 v[4:7], v[182:185], v[190:193], v[4:7]
	global_store_dwordx2 v[170:171], v[78:79], off offset:32
	s_waitcnt vmcnt(11)
	ds_write_b128 v143, v[24:27]
	ds_write_b128 v154, v[28:31] offset:10240
	ds_write_b128 v155, v[48:51] offset:28672
	v_mfma_f32_16x16x32_bf16 v[28:31], v[198:201], v[206:209], v[20:23]
	ds_write_b128 v156, v[40:43] offset:10240
	ds_write_b128 v157, v[56:59] offset:28672
	ds_write_b16 v153, v44 offset:49152
	ds_write_b16_d16_hi v153, v44 offset:49312
	ds_write_b16 v153, v45 offset:49472
	ds_write_b16_d16_hi v153, v45 offset:49632
	ds_write_b16 v153, v46 offset:49792
	ds_write_b16_d16_hi v153, v46 offset:49952
	ds_write_b16 v153, v47 offset:50112
	v_mfma_f32_16x16x32_bf16 v[74:77], v[198:201], v[210:213], v[74:77]
	ds_write_b16_d16_hi v153, v47 offset:50272
	s_ashr_i32 s35, s34, 31
	s_lshl_b64 s[36:37], s[34:35], 14
	v_mfma_f32_16x16x32_bf16 v[70:73], v[198:201], v[226:229], v[70:73]
	s_lshl_b64 s[34:35], s[34:35], 9
	s_waitcnt lgkmcnt(13)
	v_mfma_f32_16x16x32_bf16 v[170:173], v[198:201], v[214:217], v[4:7]
	s_nop 2
	v_cvt_pk_bf16_f32 v4, v28, v29
	v_cvt_pk_bf16_f32 v5, v30, v31
	v_cvt_pk_bf16_f32 v6, v74, v75
	v_cvt_pk_bf16_f32 v7, v76, v77
	ds_write2st64_b64 v158, v[4:5], v[6:7] offset0:116 offset1:125
	v_cvt_pk_bf16_f32 v4, v70, v71
	v_cvt_pk_bf16_f32 v5, v72, v73
	v_cvt_pk_bf16_f32 v6, v170, v171
	v_cvt_pk_bf16_f32 v7, v172, v173
	ds_write2st64_b64 v144, v[4:5], v[6:7] offset0:116 offset1:125
	v_add_co_u32_e32 v4, vcc, s29, v120
	s_mov_b32 s29, 0x7dc0000
	s_nop 0
	v_addc_co_u32_e32 v5, vcc, 0, v121, vcc
	v_add_co_u32_e32 v6, vcc, s29, v118
	s_waitcnt lgkmcnt(0)
	s_barrier
	ds_read_b128 v[174:177], v166
	ds_read_b128 v[178:181], v166 offset:64
	ds_read_b128 v[182:185], v145 offset:10240
	ds_read_b128 v[186:189], v145 offset:10304
	ds_read_b128 v[190:193], v145 offset:10368
	ds_read_b128 v[194:197], v145 offset:10432
	ds_read_b128 v[198:201], v160 offset:49152
	ds_read_b128 v[202:205], v160 offset:49216
	ds_read_b128 v[206:209], v159 offset:59392
	ds_read_b128 v[210:213], v159 offset:59456
	ds_read_b128 v[214:217], v159 offset:59520
	ds_read_b128 v[218:221], v159 offset:59584
	ds_read_b128 v[222:225], v160 offset:51712
	ds_read_b128 v[226:229], v160 offset:51776
	ds_read_b128 v[230:233], v159 offset:64000
	ds_read_b128 v[234:237], v159 offset:64064
	ds_read_b128 v[238:241], v159 offset:64128
	ds_read_b128 v[242:245], v159 offset:64192
	s_nop 0
	v_addc_co_u32_e32 v7, vcc, 0, v119, vcc
	s_mov_b32 s29, 0x7dd0000
	global_load_dwordx4 v[20:23], v[4:5], off
	global_load_dwordx4 v[24:27], v[6:7], off
	v_add_co_u32_e32 v4, vcc, s29, v118
	v_lshl_add_u64 v[6:7], v[92:93], 0, s[36:37]
	s_nop 0
	v_addc_co_u32_e32 v5, vcc, 0, v119, vcc
	global_load_dwordx4 v[40:43], v[4:5], off
	global_load_dwordx4 v[44:47], v[6:7], off
	v_add_co_u32_e32 v4, vcc, s46, v6
	s_mov_b32 s29, 0xbe40000
	s_nop 0
	v_addc_co_u32_e32 v5, vcc, 0, v7, vcc
	v_add_co_u32_e32 v6, vcc, s29, v122
	s_nop 1
	v_addc_co_u32_e32 v7, vcc, 0, v123, vcc
	global_load_dwordx4 v[56:59], v[4:5], off
	global_load_dwordx4 v[48:51], v[6:7], off
	v_lshl_add_u64 v[4:5], v[96:97], 0, s[34:35]
	global_load_dwordx4 v[4:7], v[4:5], off
	s_waitcnt lgkmcnt(0)
	s_waitcnt lgkmcnt(11)
	v_mfma_f32_16x16x32_bf16 v[198:201], v[198:201], v[174:177], 0
	s_waitcnt lgkmcnt(5)
	v_mfma_f32_16x16x32_bf16 v[174:177], v[222:225], v[174:177], 0
	s_waitcnt lgkmcnt(4)
	v_mfma_f32_16x16x32_bf16 v[174:177], v[226:229], v[178:181], v[174:177]
	s_waitcnt lgkmcnt(3)
	v_mfma_f32_16x16x32_bf16 v[174:177], v[230:233], v[182:185], v[174:177]
	s_waitcnt lgkmcnt(2)
	v_mfma_f32_16x16x32_bf16 v[174:177], v[234:237], v[186:189], v[174:177]
	s_waitcnt lgkmcnt(1)
	v_mfma_f32_16x16x32_bf16 v[174:177], v[238:241], v[190:193], v[174:177]
	v_mfma_f32_16x16x32_bf16 v[198:201], v[202:205], v[178:181], v[198:201]
	s_waitcnt lgkmcnt(0)
	v_mfma_f32_16x16x32_bf16 v[174:177], v[242:245], v[194:197], v[174:177]
	v_mfma_f32_16x16x32_bf16 v[178:181], v[206:209], v[182:185], v[198:201]
	ds_read_b128 v[182:185], v146 offset:28672
	s_nop 3
	ds_read_b128 v[198:201], v146 offset:28736
	ds_read_b128 v[202:205], v161 offset:49152
	ds_read_b128 v[206:209], v161 offset:49216
	v_pk_mul_f32 v[30:31], v[30:31], v[10:11]
	v_pk_mul_f32 v[28:29], v[28:29], v[8:9]
	v_mfma_f32_16x16x32_bf16 v[178:181], v[210:213], v[186:189], v[178:181]
	ds_read_b128 v[186:189], v161 offset:51712
	ds_read_b128 v[210:213], v161 offset:51776
	ds_read_b128 v[222:225], v161 offset:54272
	ds_read_b128 v[226:229], v161 offset:54336
	v_pk_mul_f32 v[76:77], v[76:77], v[10:11]
	v_pk_mul_f32 v[74:75], v[74:75], v[8:9]
	v_mfma_f32_16x16x32_bf16 v[178:181], v[214:217], v[190:193], v[178:181]
	ds_read_b128 v[190:193], v161 offset:56832
	ds_read_b128 v[214:217], v161 offset:56896
	s_waitcnt lgkmcnt(0)
	v_pk_mul_f32 v[72:73], v[72:73], v[10:11]
	v_pk_mul_f32 v[70:71], v[70:71], v[8:9]
	v_pk_mul_f32 v[10:11], v[172:173], v[10:11]
	v_pk_mul_f32 v[8:9], v[170:171], v[8:9]
	v_mfma_f32_16x16x32_bf16 v[178:181], v[218:221], v[194:197], v[178:181]
	s_waitcnt lgkmcnt(7)
	v_mfma_f32_16x16x32_bf16 v[28:31], v[182:185], v[202:205], v[28:31]
	v_add_co_u32_e32 v170, vcc, s49, v68
	s_nop 4
	v_cvt_pk_bf16_f32 v78, v178, v179
	s_waitcnt lgkmcnt(5)
	v_mfma_f32_16x16x32_bf16 v[74:77], v[182:185], v[186:189], v[74:77]
	v_cvt_pk_bf16_f32 v79, v180, v181
	v_addc_co_u32_e32 v171, vcc, 0, v69, vcc
	s_waitcnt lgkmcnt(3)
	v_mfma_f32_16x16x32_bf16 v[70:73], v[182:185], v[222:225], v[70:73]
	global_store_dwordx2 v[170:171], v[78:79], off
	v_cvt_pk_bf16_f32 v78, v174, v175
	v_cvt_pk_bf16_f32 v79, v176, v177
	s_waitcnt lgkmcnt(1)
	v_mfma_f32_16x16x32_bf16 v[8:11], v[182:185], v[190:193], v[8:11]
	global_store_dwordx2 v[170:171], v[78:79], off offset:32
	s_waitcnt vmcnt(11)
	ds_write_b128 v147, v[12:15]
	ds_write_b128 v162, v[16:19]
	ds_write_b128 v163, v[52:55]
	v_mfma_f32_16x16x32_bf16 v[170:173], v[198:201], v[206:209], v[28:31]
	ds_write_b128 v164, v[32:35]
	ds_write_b128 v165, v[64:67]
	ds_write_b16 v3, v36
	ds_write_b16_d16_hi v3, v36 offset:160
	ds_write_b16 v3, v37 offset:320
	ds_write_b16_d16_hi v3, v37 offset:480
	ds_write_b16 v3, v38 offset:640
	ds_write_b16_d16_hi v3, v38 offset:800
	ds_write_b16 v3, v39 offset:960
	v_mfma_f32_16x16x32_bf16 v[64:67], v[198:201], v[210:213], v[74:77]
	ds_write_b16_d16_hi v3, v39 offset:1120
	s_ashr_i32 s31, s30, 31
	s_lshl_b64 s[34:35], s[30:31], 14
	v_mfma_f32_16x16x32_bf16 v[70:73], v[198:201], v[226:229], v[70:73]
	s_waitcnt lgkmcnt(13)
	v_mfma_f32_16x16x32_bf16 v[74:77], v[198:201], v[214:217], v[8:11]
	s_nop 2
	v_cvt_pk_bf16_f32 v8, v170, v171
	v_cvt_pk_bf16_f32 v9, v172, v173
	v_cvt_pk_bf16_f32 v10, v64, v65
	v_cvt_pk_bf16_f32 v11, v66, v67
	ds_write2st64_b64 v148, v[8:9], v[10:11] offset1:9
	v_cvt_pk_bf16_f32 v8, v70, v71
	v_cvt_pk_bf16_f32 v9, v72, v73
	v_cvt_pk_bf16_f32 v10, v74, v75
	v_cvt_pk_bf16_f32 v11, v76, v77
	ds_write2st64_b64 v148, v[8:9], v[10:11] offset0:18 offset1:27
	v_add_co_u32_e32 v8, vcc, s51, v120
	s_waitcnt lgkmcnt(0)
	s_barrier
	s_nop 0
	v_addc_co_u32_e32 v9, vcc, 0, v121, vcc
	v_add_co_u32_e32 v10, vcc, s52, v118
	s_nop 1
	v_addc_co_u32_e32 v11, vcc, 0, v119, vcc
	global_load_dwordx4 v[12:15], v[8:9], off
	global_load_dwordx4 v[16:19], v[10:11], off
	v_add_co_u32_e32 v8, vcc, s53, v118
	v_lshl_add_u64 v[10:11], v[92:93], 0, s[34:35]
	s_nop 0
	v_addc_co_u32_e32 v9, vcc, 0, v119, vcc
	global_load_dwordx4 v[28:31], v[8:9], off
	global_load_dwordx4 v[36:39], v[10:11], off
	v_add_co_u32_e32 v8, vcc, s46, v10
	s_lshl_b64 s[34:35], s[30:31], 9
	s_nop 0
	v_addc_co_u32_e32 v9, vcc, 0, v11, vcc
	v_add_co_u32_e32 v10, vcc, s55, v122
	s_nop 1
	v_addc_co_u32_e32 v11, vcc, 0, v123, vcc
	global_load_dwordx4 v[52:55], v[8:9], off
	global_load_dwordx4 v[32:35], v[10:11], off
	v_lshl_add_u64 v[8:9], v[96:97], 0, s[34:35]
	global_load_dwordx4 v[8:11], v[8:9], off
	ds_read_b128 v[118:121], v149
	ds_read_b128 v[174:177], v149 offset:64
	ds_read_b128 v[178:181], v150
	ds_read_b128 v[182:185], v150 offset:64
	ds_read_b128 v[186:189], v150 offset:128
	ds_read_b128 v[190:193], v150 offset:192
	ds_read_b128 v[194:197], v168
	ds_read_b128 v[198:201], v168 offset:64
	ds_read_b128 v[202:205], v151
	ds_read_b128 v[206:209], v151 offset:64
	ds_read_b128 v[210:213], v151 offset:128
	ds_read_b128 v[214:217], v151 offset:192
	ds_read_b128 v[218:221], v168 offset:2560
	ds_read_b128 v[222:225], v168 offset:2624
	ds_read_b128 v[226:229], v151 offset:4608
	ds_read_b128 v[230:233], v151 offset:4672
	ds_read_b128 v[234:237], v151 offset:4736
	ds_read_b128 v[238:241], v151 offset:4800
	s_waitcnt lgkmcnt(0)
	s_waitcnt lgkmcnt(11)
	v_mfma_f32_16x16x32_bf16 v[194:197], v[194:197], v[118:121], 0
	s_waitcnt lgkmcnt(5)
	v_mfma_f32_16x16x32_bf16 v[118:121], v[218:221], v[118:121], 0
	s_waitcnt lgkmcnt(4)
	v_mfma_f32_16x16x32_bf16 v[118:121], v[222:225], v[174:177], v[118:121]
	s_waitcnt lgkmcnt(3)
	v_mfma_f32_16x16x32_bf16 v[118:121], v[226:229], v[178:181], v[118:121]
	s_waitcnt lgkmcnt(2)
	v_mfma_f32_16x16x32_bf16 v[118:121], v[230:233], v[182:185], v[118:121]
	s_waitcnt lgkmcnt(1)
; #define LDS_BAR() do { asm volatile("s_waitcnt lgkmcnt(0)" ::: "memory"); __builtin_amdgcn_s_barrier(); asm volatile("" ::: "memory"); } while (0)
; #define H2_LOADC(R, cc) do { const int c_ = (cc) < nch ? (cc) : nch - 1; \
;         h2_load<SAMP>(R, a, OF, SAMP ? MP + b * DEC_T : b * SEQ + c_ * 64, SAMP ? NB * 64 * GH + bh : (b * 64 + c_) * GH + h, h, es, tid, lane); } while (0)
; template <bool SAMP> __device__ __forceinline__ void g2_item(const Args& a, Frame& F, int bh, int es) {
;     ...
;     H2_LOADC(R0, 0); if (!SAMP) H2_LOADC(R1, 1);
;     LDS_BAR();
;     if (SAMP) { H2_STEP(R0, R2, 0, 0); }
;     else {
;         H2_STEP(R0, R2, 0, 0); H2_STEP(R1, R0, 1, 1);
;         for (int c = 2; c < 62; c += 6) { H2_STEP(R2, R1, c, 0); H2_STEP(R0, R2, c + 1, 1); H2_STEP(R1, R0, c + 2, 0); H2_STEP(R2, R1, c + 3, 1); H2_STEP(R0, R2, c + 4, 0); H2_STEP(R1, R0, c + 5, 1); }
;         H2_STEP(R2, R1, 62, 0); H2_STEP(R0, R2, 63, 1);
	v_mfma_f32_16x16x32_bf16 v[118:121], v[234:237], v[186:189], v[118:121]
	v_mfma_f32_16x16x32_bf16 v[194:197], v[198:201], v[174:177], v[194:197]
	s_waitcnt lgkmcnt(0)
	v_mfma_f32_16x16x32_bf16 v[118:121], v[238:241], v[190:193], v[118:121]
	v_mfma_f32_16x16x32_bf16 v[174:177], v[202:205], v[178:181], v[194:197]
	ds_read_b128 v[178:181], v152
	s_nop 3
	ds_read_b128 v[194:197], v152 offset:64
	ds_read_b128 v[198:201], v167
	ds_read_b128 v[202:205], v167 offset:64
	v_pk_mul_f32 v[172:173], v[172:173], v[62:63]
	v_pk_mul_f32 v[170:171], v[170:171], v[60:61]
	v_mfma_f32_16x16x32_bf16 v[174:177], v[206:209], v[182:185], v[174:177]
	ds_read_b128 v[182:185], v167 offset:2560
	ds_read_b128 v[206:209], v167 offset:2624
	ds_read_b128 v[218:221], v167 offset:5120
	ds_read_b128 v[222:225], v167 offset:5184
	v_pk_mul_f32 v[66:67], v[66:67], v[62:63]
	v_pk_mul_f32 v[64:65], v[64:65], v[60:61]
	v_mfma_f32_16x16x32_bf16 v[174:177], v[210:213], v[186:189], v[174:177]
	ds_read_b128 v[186:189], v167 offset:7680
	ds_read_b128 v[210:213], v167 offset:7744
	s_waitcnt lgkmcnt(0)
	v_pk_mul_f32 v[72:73], v[72:73], v[62:63]
	v_pk_mul_f32 v[70:71], v[70:71], v[60:61]
	v_pk_mul_f32 v[62:63], v[76:77], v[62:63]
	v_pk_mul_f32 v[60:61], v[74:75], v[60:61]
	v_mfma_f32_16x16x32_bf16 v[174:177], v[214:217], v[190:193], v[174:177]
	s_waitcnt lgkmcnt(7)
	v_mfma_f32_16x16x32_bf16 v[74:77], v[178:181], v[198:201], v[170:173]
	s_add_i32 s21, s21, 6
	s_add_i32 s30, s30, 24
	v_lshl_add_u64 v[110:111], v[110:111], 0, s[16:17]
	s_waitcnt lgkmcnt(5)
	v_mfma_f32_16x16x32_bf16 v[170:173], v[178:181], v[182:185], v[64:67]
	v_lshl_add_u64 v[112:113], v[112:113], 0, s[16:17]
	v_lshl_add_u64 v[114:115], v[114:115], 0, s[18:19]
	v_lshl_add_u64 v[116:117], v[116:117], 0, s[16:17]
	s_waitcnt lgkmcnt(3)
	v_mfma_f32_16x16x32_bf16 v[70:73], v[178:181], v[218:221], v[70:73]
	v_cvt_pk_bf16_f32 v64, v174, v175
	v_cvt_pk_bf16_f32 v65, v176, v177
	s_cmp_lt_u32 s21, 56
	s_waitcnt lgkmcnt(1)
	v_mfma_f32_16x16x32_bf16 v[174:177], v[178:181], v[186:189], v[60:63]
	s_nop 2
	v_add_co_u32_e32 v60, vcc, s50, v68
	v_cvt_pk_bf16_f32 v62, v118, v119
	s_nop 0
	v_addc_co_u32_e32 v61, vcc, 0, v69, vcc
	v_cvt_pk_bf16_f32 v63, v120, v121
	global_store_dwordx2 v[60:61], v[64:65], off
	v_mfma_f32_16x16x32_bf16 v[64:67], v[194:197], v[202:205], v[74:77]
	global_store_dwordx2 v[60:61], v[62:63], off offset:32
	v_mfma_f32_16x16x32_bf16 v[60:63], v[194:197], v[206:209], v[170:173]
	v_mfma_f32_16x16x32_bf16 v[68:71], v[194:197], v[222:225], v[70:73]
	s_waitcnt lgkmcnt(0)
	v_mfma_f32_16x16x32_bf16 v[72:75], v[194:197], v[210:213], v[174:177]
	s_cbranch_scc1 .LBB0_1356
	s_waitcnt vmcnt(11)
	ds_write_b128 v143, v[20:23]
	ds_write_b128 v154, v[24:27] offset:10240
	ds_write_b128 v155, v[44:47] offset:28672
	ds_write_b128 v156, v[40:43] offset:10240
	ds_write_b128 v157, v[56:59] offset:28672
	ds_write_b16 v153, v48 offset:49152
	ds_write_b16_d16_hi v153, v48 offset:49312
	ds_write_b16 v153, v49 offset:49472
	ds_write_b16_d16_hi v153, v49 offset:49632
	ds_write_b16 v153, v50 offset:49792
	ds_write_b16_d16_hi v153, v50 offset:49952
	ds_write_b16 v153, v51 offset:50112
	ds_write_b16_d16_hi v153, v51 offset:50272
	v_cvt_pk_bf16_f32 v20, v64, v65
	v_cvt_pk_bf16_f32 v21, v66, v67
	v_cvt_pk_bf16_f32 v22, v60, v61
	v_cvt_pk_bf16_f32 v23, v62, v63
	ds_write2st64_b64 v158, v[20:21], v[22:23] offset0:116 offset1:125
	v_cvt_pk_bf16_f32 v20, v68, v69
	v_cvt_pk_bf16_f32 v21, v70, v71
	v_cvt_pk_bf16_f32 v22, v72, v73
	v_cvt_pk_bf16_f32 v23, v74, v75
	ds_write2st64_b64 v144, v[20:21], v[22:23] offset0:116 offset1:125
	s_waitcnt lgkmcnt(0)
	s_barrier
	ds_read_b128 v[20:23], v166
	ds_read_b128 v[24:27], v166 offset:64
	ds_read_b128 v[40:43], v145 offset:10240
	ds_read_b128 v[44:47], v145 offset:10304
	ds_read_b128 v[48:51], v145 offset:10368
	ds_read_b128 v[56:59], v145 offset:10432
	ds_read_b128 v[76:79], v160 offset:49152
	ds_read_b128 v[110:113], v160 offset:49216
	ds_read_b128 v[114:117], v159 offset:59392
	ds_read_b128 v[118:121], v159 offset:59456
	ds_read_b128 v[170:173], v159 offset:59520
	ds_read_b128 v[174:177], v159 offset:59584
	ds_read_b128 v[178:181], v160 offset:51712
	ds_read_b128 v[182:185], v160 offset:51776
	ds_read_b128 v[186:189], v159 offset:64000
	ds_read_b128 v[190:193], v159 offset:64064
	ds_read_b128 v[194:197], v159 offset:64128
	ds_read_b128 v[198:201], v159 offset:64192
	s_waitcnt lgkmcnt(0)
	s_or_b32 s30, s28, 0xf80
	s_or_b32 s28, s28, 0xfc0
	s_ashr_i32 s29, s28, 31
	s_waitcnt lgkmcnt(11)
	v_mfma_f32_16x16x32_bf16 v[76:79], v[76:79], v[20:23], 0
	s_waitcnt lgkmcnt(5)
	v_mfma_f32_16x16x32_bf16 v[20:23], v[178:181], v[20:23], 0
	s_waitcnt lgkmcnt(4)
	v_mfma_f32_16x16x32_bf16 v[20:23], v[182:185], v[24:27], v[20:23]
	s_waitcnt lgkmcnt(3)
	v_mfma_f32_16x16x32_bf16 v[20:23], v[186:189], v[40:43], v[20:23]
	s_waitcnt lgkmcnt(2)
	v_mfma_f32_16x16x32_bf16 v[20:23], v[190:193], v[44:47], v[20:23]
	s_waitcnt lgkmcnt(1)
	v_mfma_f32_16x16x32_bf16 v[20:23], v[194:197], v[48:51], v[20:23]
	v_mfma_f32_16x16x32_bf16 v[76:79], v[110:113], v[24:27], v[76:79]
	s_waitcnt lgkmcnt(0)
	v_mfma_f32_16x16x32_bf16 v[20:23], v[198:201], v[56:59], v[20:23]
	v_mfma_f32_16x16x32_bf16 v[24:27], v[114:117], v[40:43], v[76:79]
	ds_read_b128 v[40:43], v146 offset:28672
	s_nop 3
	ds_read_b128 v[76:79], v146 offset:28736
	ds_read_b128 v[110:113], v161 offset:49152
	ds_read_b128 v[114:117], v161 offset:49216
	v_pk_mul_f32 v[66:67], v[66:67], v[6:7]
	v_pk_mul_f32 v[64:65], v[64:65], v[4:5]
	v_mfma_f32_16x16x32_bf16 v[24:27], v[118:121], v[44:47], v[24:27]
	ds_read_b128 v[44:47], v161 offset:51712
	ds_read_b128 v[118:121], v161 offset:51776
	ds_read_b128 v[178:181], v161 offset:54272
	ds_read_b128 v[182:185], v161 offset:54336
	v_mfma_f32_16x16x32_bf16 v[24:27], v[170:173], v[48:51], v[24:27]
	ds_read_b128 v[48:51], v161 offset:56832
	ds_read_b128 v[170:173], v161 offset:56896
	s_waitcnt lgkmcnt(0)
; #define LDS_BAR() do { asm volatile("s_waitcnt lgkmcnt(0)" ::: "memory"); __builtin_amdgcn_s_barrier(); asm volatile("" ::: "memory"); } while (0)
; #define H2_LOADC(R, cc) do { const int c_ = (cc) < nch ? (cc) : nch - 1; \
;         h2_load<SAMP>(R, a, OF, SAMP ? MP + b * DEC_T : b * SEQ + c_ * 64, SAMP ? NB * 64 * GH + bh : (b * 64 + c_) * GH + h, h, es, tid, lane); } while (0)
; #define S xcd_barrier(bar);
; template <bool SAMP> __device__ __forceinline__ void g2_item(const Args& a, Frame& F, int bh, int es) {
;     ...
;     H2_LOADC(R0, 0); if (!SAMP) H2_LOADC(R1, 1);
;     LDS_BAR();
;     if (SAMP) { H2_STEP(R0, R2, 0, 0); }
;     else {
;         H2_STEP(R0, R2, 0, 0); H2_STEP(R1, R0, 1, 1);
;         for (int c = 2; c < 62; c += 6) { H2_STEP(R2, R1, c, 0); H2_STEP(R0, R2, c + 1, 1); H2_STEP(R1, R0, c + 2, 0); H2_STEP(R2, R1, c + 3, 1); H2_STEP(R0, R2, c + 4, 0); H2_STEP(R1, R0, c + 5, 1); }
;         H2_STEP(R2, R1, 62, 0); H2_STEP(R0, R2, 63, 1);
;     }
;     ...
;     float* so = a.out + (SAMP ? O_SGS : O_SGP);
; #pragma unroll
;     for (int eb = 0; eb < 4; ++eb)
; #pragma unroll
;         for (int r = 0; r < 4; ++r) so[((size_t)bh * 128 + 16 * wave + 4 * fq + r) * 256 + es * 64 + eb * 16 + fr] = S[eb][r];
	v_mfma_f32_16x16x32_bf16 v[24:27], v[174:177], v[56:59], v[24:27]
	v_mul_f32_e64 v58, v62, v6
	v_mul_f32_e64 v59, v63, v7
	v_pk_mul_f32 v[56:57], v[60:61], v[4:5]
	v_pk_mul_f32 v[62:63], v[70:71], v[6:7]
	v_pk_mul_f32 v[60:61], v[68:69], v[4:5]
	v_pk_mul_f32 v[6:7], v[74:75], v[6:7]
	v_pk_mul_f32 v[4:5], v[72:73], v[4:5]
	s_ashr_i32 s31, s30, 31
	s_lshl_b64 s[30:31], s[30:31], 10
	v_cvt_pk_bf16_f32 v68, v24, v25
	v_cvt_pk_bf16_f32 v69, v26, v27
	s_waitcnt lgkmcnt(7)
	v_mfma_f32_16x16x32_bf16 v[24:27], v[40:43], v[110:113], v[64:67]
	s_or_b64 s[30:31], s[30:31], s[26:27]
	s_or_b64 s[30:31], s[30:31], s[24:25]
	v_cvt_pk_bf16_f32 v20, v20, v21
	s_waitcnt lgkmcnt(5)
	v_mfma_f32_16x16x32_bf16 v[44:47], v[40:43], v[44:47], v[56:59]
	v_lshl_add_u64 v[64:65], s[30:31], 1, v[98:99]
	v_cvt_pk_bf16_f32 v21, v22, v23
	global_store_dwordx2 v[64:65], v[68:69], off
	s_waitcnt lgkmcnt(3)
	v_mfma_f32_16x16x32_bf16 v[56:59], v[40:43], v[178:181], v[60:63]
	global_store_dwordx2 v[64:65], v[20:21], off offset:32
	s_waitcnt vmcnt(4)
	ds_write_b128 v147, v[12:15]
	ds_write_b128 v162, v[16:19]
	s_waitcnt lgkmcnt(3)
	v_mfma_f32_16x16x32_bf16 v[4:7], v[40:43], v[48:51], v[4:7]
	ds_write_b128 v163, v[36:39]
	ds_write_b128 v164, v[28:31]
	ds_write_b128 v165, v[52:55]
	ds_write_b16 v3, v32
	ds_write_b16_d16_hi v3, v32 offset:160
	ds_write_b16 v3, v33 offset:320
	ds_write_b16_d16_hi v3, v33 offset:480
	ds_write_b16 v3, v34 offset:640
	ds_write_b16_d16_hi v3, v34 offset:800
	v_mfma_f32_16x16x32_bf16 v[12:15], v[76:79], v[114:117], v[24:27]
	ds_write_b16 v3, v35 offset:960
	ds_write_b16_d16_hi v3, v35 offset:1120
	s_lshl_b64 s[28:29], s[28:29], 10
	v_mfma_f32_16x16x32_bf16 v[16:19], v[76:79], v[118:121], v[44:47]
	s_nop 3
	v_cvt_pk_bf16_f32 v24, v12, v13
	v_cvt_pk_bf16_f32 v25, v14, v15
	v_mfma_f32_16x16x32_bf16 v[20:23], v[76:79], v[182:185], v[56:59]
	s_waitcnt lgkmcnt(13)
	v_mfma_f32_16x16x32_bf16 v[4:7], v[76:79], v[170:173], v[4:7]
	v_cvt_pk_bf16_f32 v26, v16, v17
	v_cvt_pk_bf16_f32 v27, v18, v19
	ds_write2st64_b64 v148, v[24:25], v[26:27] offset1:9
	s_nop 2
	v_cvt_pk_bf16_f32 v24, v20, v21
	v_cvt_pk_bf16_f32 v25, v22, v23
	v_cvt_pk_bf16_f32 v26, v4, v5
	v_cvt_pk_bf16_f32 v27, v6, v7
	ds_write2st64_b64 v148, v[24:25], v[26:27] offset0:18 offset1:27
	s_waitcnt lgkmcnt(0)
	s_barrier
	ds_read_b128 v[24:27], v149
	ds_read_b128 v[28:31], v149 offset:64
	ds_read_b128 v[32:35], v150
	ds_read_b128 v[36:39], v150 offset:64
	ds_read_b128 v[40:43], v150 offset:128
	ds_read_b128 v[44:47], v150 offset:192
	ds_read_b128 v[48:51], v168
	ds_read_b128 v[52:55], v168 offset:64
	ds_read_b128 v[56:59], v151
	ds_read_b128 v[60:63], v151 offset:64
	ds_read_b128 v[64:67], v151 offset:128
	ds_read_b128 v[68:71], v151 offset:192
	ds_read_b128 v[72:75], v168 offset:2560
	ds_read_b128 v[76:79], v168 offset:2624
	ds_read_b128 v[110:113], v151 offset:4608
	ds_read_b128 v[114:117], v151 offset:4672
	ds_read_b128 v[118:121], v151 offset:4736
	ds_read_b128 v[162:165], v151 offset:4800
	s_waitcnt lgkmcnt(0)
	s_waitcnt lgkmcnt(11)
	v_mfma_f32_16x16x32_bf16 v[48:51], v[48:51], v[24:27], 0
	s_waitcnt lgkmcnt(5)
	v_mfma_f32_16x16x32_bf16 v[24:27], v[72:75], v[24:27], 0
	s_waitcnt lgkmcnt(4)
	v_mfma_f32_16x16x32_bf16 v[24:27], v[76:79], v[28:31], v[24:27]
	s_waitcnt lgkmcnt(3)
	v_mfma_f32_16x16x32_bf16 v[24:27], v[110:113], v[32:35], v[24:27]
	s_waitcnt lgkmcnt(2)
	v_mfma_f32_16x16x32_bf16 v[24:27], v[114:117], v[36:39], v[24:27]
	s_waitcnt lgkmcnt(1)
	v_mfma_f32_16x16x32_bf16 v[24:27], v[118:121], v[40:43], v[24:27]
	v_mfma_f32_16x16x32_bf16 v[48:51], v[52:55], v[28:31], v[48:51]
	s_waitcnt lgkmcnt(0)
	v_mfma_f32_16x16x32_bf16 v[24:27], v[162:165], v[44:47], v[24:27]
	v_mfma_f32_16x16x32_bf16 v[28:31], v[56:59], v[32:35], v[48:51]
	ds_read_b128 v[32:35], v152
	s_nop 3
	ds_read_b128 v[48:51], v152 offset:64
	ds_read_b128 v[52:55], v167
	ds_read_b128 v[56:59], v167 offset:64
	v_pk_mul_f32 v[14:15], v[14:15], v[10:11]
	v_pk_mul_f32 v[12:13], v[12:13], v[8:9]
	v_mfma_f32_16x16x32_bf16 v[28:31], v[60:63], v[36:39], v[28:31]
	ds_read_b128 v[36:39], v167 offset:2560
	ds_read_b128 v[60:63], v167 offset:2624
	ds_read_b128 v[72:75], v167 offset:5120
	ds_read_b128 v[76:79], v167 offset:5184
	v_pk_mul_f32 v[18:19], v[18:19], v[10:11]
	v_pk_mul_f32 v[16:17], v[16:17], v[8:9]
	v_mfma_f32_16x16x32_bf16 v[28:31], v[64:67], v[40:43], v[28:31]
	ds_read_b128 v[40:43], v167 offset:7680
	ds_read_b128 v[64:67], v167 offset:7744
	s_waitcnt lgkmcnt(0)
	v_pk_mul_f32 v[22:23], v[22:23], v[10:11]
	v_mfma_f32_16x16x32_bf16 v[28:31], v[68:71], v[44:47], v[28:31]
	v_mul_f32_e64 v20, v20, v8
	v_mul_f32_e64 v21, v21, v9
	v_pk_mul_f32 v[6:7], v[6:7], v[10:11]
	v_pk_mul_f32 v[4:5], v[4:5], v[8:9]
	s_waitcnt lgkmcnt(7)
	v_mfma_f32_16x16x32_bf16 v[8:11], v[32:35], v[52:55], v[12:15]
	s_or_b64 s[26:27], s[28:29], s[26:27]
	s_or_b64 s[26:27], s[26:27], s[24:25]
	s_ashr_i32 s21, s20, 31
	s_waitcnt lgkmcnt(5)
	v_mfma_f32_16x16x32_bf16 v[12:15], v[32:35], v[36:39], v[16:19]
	v_cvt_pk_bf16_f32 v28, v28, v29
	v_cvt_pk_bf16_f32 v29, v30, v31
	v_lshl_add_u64 v[30:31], s[26:27], 1, v[98:99]
	s_waitcnt lgkmcnt(3)
	v_mfma_f32_16x16x32_bf16 v[16:19], v[32:35], v[72:75], v[20:23]
	s_lshl_b32 s24, s24, 2
	s_mov_b32 s25, s11
	s_lshl_b64 s[26:27], s[20:21], 17
	v_mfma_f32_16x16x32_bf16 v[8:11], v[48:51], v[56:59], v[8:11]
	global_store_dwordx2 v[30:31], v[28:29], off
	v_lshl_add_u64 v[20:21], v[102:103], 0, s[24:25]
	v_lshl_add_u64 v[28:29], s[26:27], 0, v[88:89]
	v_cvt_pk_bf16_f32 v24, v24, v25
	v_cvt_pk_bf16_f32 v25, v26, v27
	s_waitcnt lgkmcnt(1)
	v_mfma_f32_16x16x32_bf16 v[4:7], v[32:35], v[40:43], v[4:7]
	v_lshl_add_u64 v[20:21], v[20:21], 0, v[28:29]
	global_store_dwordx2 v[30:31], v[24:25], off offset:32
	global_store_dword v[20:21], v8, off
	v_mfma_f32_16x16x32_bf16 v[12:15], v[48:51], v[60:63], v[12:15]
	global_store_dword v[20:21], v9, off offset:1024
	global_store_dword v[20:21], v10, off offset:2048
	global_store_dword v[20:21], v11, off offset:3072
	s_nop 4
	global_store_dword v[20:21], v12, off offset:64
	global_store_dword v[20:21], v13, off offset:1088
	global_store_dword v[20:21], v14, off offset:2112
	v_mfma_f32_16x16x32_bf16 v[8:11], v[48:51], v[76:79], v[16:19]
	s_waitcnt lgkmcnt(0)
	v_mfma_f32_16x16x32_bf16 v[4:7], v[48:51], v[64:67], v[4:7]
	global_store_dword v[20:21], v15, off offset:3136
	s_nop 4
	global_store_dword v[20:21], v8, off offset:128
	global_store_dword v[20:21], v9, off offset:1152
	global_store_dword v[20:21], v10, off offset:2176
	global_store_dword v[20:21], v11, off offset:3200
	global_store_dword v[20:21], v4, off offset:192
	global_store_dword v[20:21], v5, off offset:1216
	global_store_dword v[20:21], v6, off offset:2240
	global_store_dword v[20:21], v7, off offset:3264
	s_and_saveexec_b64 s[26:27], s[4:5]
	s_cbranch_execz .LBB0_1367
	s_mov_b32 s21, 0x400001
	s_branch .LBB0_1360
